# non-temporal (nt) streaming hints on the deferred conversion loop's loads and stores, on top of the s_sleep 64 throttle
# speedup vs baseline: 1.0126x; 1.0126x over previous
; __device__ __forceinline__ int tid_() { int t = threadIdx.x; asm volatile("" : "+v"(t)); return t; }
; __device__ __forceinline__ void conv_table_chunk4(const float* __restrict__ src, unsigned char* __restrict__ dst, size_t base, float scale) {
;   f32x4 a[4], b[4];
; #pragma unroll
;   for (int q = 0; q < 4; ++q) {
;     size_t i = base + (size_t)q * 2048 + (size_t)tid_() * 8;
;     a[q] = *(const f32x4*)(src + i); b[q] = *(const f32x4*)(src + i + 4);
;   }
; #pragma unroll
;   for (int q = 0; q < 4; ++q) {
;     size_t i = base + (size_t)q * 2048 + (size_t)tid_() * 8;
;     int w0 = 0, w1 = 0;
;     w0 = __builtin_amdgcn_cvt_pk_fp8_f32(a[q][0] * scale, a[q][1] * scale, w0, false);
;     w0 = __builtin_amdgcn_cvt_pk_fp8_f32(a[q][2] * scale, a[q][3] * scale, w0, true);
;     w1 = __builtin_amdgcn_cvt_pk_fp8_f32(b[q][0] * scale, b[q][1] * scale, w1, false);
;     w1 = __builtin_amdgcn_cvt_pk_fp8_f32(b[q][2] * scale, b[q][3] * scale, w1, true);
;     size_t e = i >> 10; int col = (int)(i & 1023); int x = col >> 7;
;     *(uint2*)(dst + ((size_t)x * 16384 + e) * 128 + (col & 127)) = make_uint2((unsigned)w0, (unsigned)w1);
;   }
; }
.Ldef_tab:
	s_mov_b32 s53, 0
	s_lshl_b64 s[60:61], s[52:53], 15
	s_add_u32 s54, s54, s60
	s_addc_u32 s55, s55, s61
	s_lshl_b32 s60, s52, 10
	s_add_u32 s60, s60, s59
	s_add_u32 s56, s40, s60
	s_addc_u32 s57, s41, 0
	global_load_dwordx4 v[16:19], v1, s[54:55] nt
	global_load_dwordx4 v[20:23], v1, s[54:55] offset:16 nt
	global_load_dwordx4 v[24:27], v5, s[54:55] nt
	global_load_dwordx4 v[28:31], v5, s[54:55] offset:16 nt
	global_load_dwordx4 v[32:35], v6, s[54:55] nt
	global_load_dwordx4 v[36:39], v6, s[54:55] offset:16 nt
	global_load_dwordx4 v[40:43], v7, s[54:55] nt
	global_load_dwordx4 v[44:47], v7, s[54:55] offset:16 nt
	s_waitcnt vmcnt(6)
	v_mul_f32_e32 v16, s58, v16
	v_mul_f32_e32 v17, s58, v17
	v_mul_f32_e32 v18, s58, v18
	v_mul_f32_e32 v19, s58, v19
	v_mul_f32_e32 v20, s58, v20
	v_mul_f32_e32 v21, s58, v21
	v_mul_f32_e32 v22, s58, v22
	v_mul_f32_e32 v23, s58, v23
	v_mov_b32_e32 v48, 0
	v_mov_b32_e32 v49, 0
	v_cvt_pk_fp8_f32 v48, v16, v17
	v_cvt_pk_fp8_f32 v49, v20, v21
	s_nop 0
	v_cvt_pk_fp8_f32 v48, v18, v19 op_sel:[0,0,1]
	v_cvt_pk_fp8_f32 v49, v22, v23 op_sel:[0,0,1]
	s_nop 1
	global_store_dwordx2 v2, v[48:49], s[56:57] offset:0 nt
	s_waitcnt vmcnt(4)
	v_mul_f32_e32 v24, s58, v24
	v_mul_f32_e32 v25, s58, v25
	v_mul_f32_e32 v26, s58, v26
	v_mul_f32_e32 v27, s58, v27
	v_mul_f32_e32 v28, s58, v28
	v_mul_f32_e32 v29, s58, v29
	v_mul_f32_e32 v30, s58, v30
	v_mul_f32_e32 v31, s58, v31
	v_mov_b32_e32 v50, 0
	v_mov_b32_e32 v51, 0
	v_cvt_pk_fp8_f32 v50, v24, v25
	v_cvt_pk_fp8_f32 v51, v28, v29
	s_nop 0
	v_cvt_pk_fp8_f32 v50, v26, v27 op_sel:[0,0,1]
	v_cvt_pk_fp8_f32 v51, v30, v31 op_sel:[0,0,1]
	s_nop 1
	global_store_dwordx2 v2, v[50:51], s[56:57] offset:256 nt
	s_waitcnt vmcnt(2)
	v_mul_f32_e32 v32, s58, v32
	v_mul_f32_e32 v33, s58, v33
	v_mul_f32_e32 v34, s58, v34
	v_mul_f32_e32 v35, s58, v35
	v_mul_f32_e32 v36, s58, v36
	v_mul_f32_e32 v37, s58, v37
	v_mul_f32_e32 v38, s58, v38
	v_mul_f32_e32 v39, s58, v39
	v_mov_b32_e32 v52, 0
	v_mov_b32_e32 v53, 0
	v_cvt_pk_fp8_f32 v52, v32, v33
	v_cvt_pk_fp8_f32 v53, v36, v37
	s_nop 0
	v_cvt_pk_fp8_f32 v52, v34, v35 op_sel:[0,0,1]
	v_cvt_pk_fp8_f32 v53, v38, v39 op_sel:[0,0,1]
	s_nop 1
	global_store_dwordx2 v2, v[52:53], s[56:57] offset:512 nt
	s_waitcnt vmcnt(0)
	v_mul_f32_e32 v40, s58, v40
	v_mul_f32_e32 v41, s58, v41
	v_mul_f32_e32 v42, s58, v42
	v_mul_f32_e32 v43, s58, v43
	v_mul_f32_e32 v44, s58, v44
	v_mul_f32_e32 v45, s58, v45
	v_mul_f32_e32 v46, s58, v46
	v_mul_f32_e32 v47, s58, v47
	v_mov_b32_e32 v54, 0
	v_mov_b32_e32 v55, 0
	v_cvt_pk_fp8_f32 v54, v40, v41
	v_cvt_pk_fp8_f32 v55, v44, v45
	s_nop 0
	v_cvt_pk_fp8_f32 v54, v42, v43 op_sel:[0,0,1]
	v_cvt_pk_fp8_f32 v55, v46, v47 op_sel:[0,0,1]
	s_nop 1
	global_store_dwordx2 v2, v[54:55], s[56:57] offset:768 nt
	s_branch .Ldef_next

; __device__ __forceinline__ int tid_() { int t = threadIdx.x; asm volatile("" : "+v"(t)); return t; }
; __device__ __forceinline__ void conv_chunk4(const float* __restrict__ src, u16* __restrict__ dst, size_t base) {
;   f32x4 a[4], b[4];
; #pragma unroll
;   for (int q = 0; q < 4; ++q) {
;     size_t i = base + (size_t)q * 2048 + (size_t)tid_() * 8;
;     a[q] = *(const f32x4*)(src + i); b[q] = *(const f32x4*)(src + i + 4);
;   }
; #pragma unroll
;   for (int q = 0; q < 4; ++q) {
;     size_t i = base + (size_t)q * 2048 + (size_t)tid_() * 8;
;     BF8 t; t.u[0] = pack2(a[q][0], a[q][1]); t.u[1] = pack2(a[q][2], a[q][3]); t.u[2] = pack2(b[q][0], b[q][1]); t.u[3] = pack2(b[q][2], b[q][3]);
;     *(uint4*)(dst + i) = t.q;
;   }
; }
.Ldef_psrc:
	s_lshl_b64 s[60:61], s[52:53], 15
	s_add_u32 s54, s54, s60
	s_addc_u32 s55, s55, s61
	global_load_dwordx4 v[16:19], v1, s[54:55] nt
	global_load_dwordx4 v[20:23], v1, s[54:55] offset:16 nt
	global_load_dwordx4 v[24:27], v5, s[54:55] nt
	global_load_dwordx4 v[28:31], v5, s[54:55] offset:16 nt
	global_load_dwordx4 v[32:35], v6, s[54:55] nt
	global_load_dwordx4 v[36:39], v6, s[54:55] offset:16 nt
	global_load_dwordx4 v[40:43], v7, s[54:55] nt
	global_load_dwordx4 v[44:47], v7, s[54:55] offset:16 nt
	s_waitcnt vmcnt(6)
	v_cvt_pk_bf16_f32 v48, v16, v17
	v_cvt_pk_bf16_f32 v49, v18, v19
	v_cvt_pk_bf16_f32 v50, v20, v21
	v_cvt_pk_bf16_f32 v51, v22, v23
	global_store_dwordx4 v3, v[48:51], s[56:57] nt
	s_waitcnt vmcnt(4)
	v_cvt_pk_bf16_f32 v52, v24, v25
	v_cvt_pk_bf16_f32 v53, v26, v27
	v_cvt_pk_bf16_f32 v54, v28, v29
	v_cvt_pk_bf16_f32 v55, v30, v31
	global_store_dwordx4 v9, v[52:55], s[56:57] nt
	s_waitcnt vmcnt(2)
	v_cvt_pk_bf16_f32 v48, v32, v33
	v_cvt_pk_bf16_f32 v49, v34, v35
	v_cvt_pk_bf16_f32 v50, v36, v37
	v_cvt_pk_bf16_f32 v51, v38, v39
	global_store_dwordx4 v10, v[48:51], s[56:57] nt
	s_waitcnt vmcnt(0)
	v_cvt_pk_bf16_f32 v52, v40, v41
	v_cvt_pk_bf16_f32 v53, v42, v43
	v_cvt_pk_bf16_f32 v54, v44, v45
	v_cvt_pk_bf16_f32 v55, v46, v47
	global_store_dwordx4 v11, v[52:55], s[56:57] nt
